# attention static prio for waves 0-3 instead of 4-7 (A/B of v7)
# baseline (speedup 1.0000x reference)
.LBB0_672:
	s_andn2_b64 vcc, exec, s[2:3]
	s_cbranch_vccnz .LBB0_698
	v_max_f32_e32 v3, v5, v5
	v_mul_u32_u24_e32 v2, 0x90, v2
	v_max_f32_e32 v199, v4, v3
	v_add3_u32 v200, 0, v2, v0
	v_sub_f32_e32 v0, v16, v199
	v_exp_f32_e32 v16, v0
	v_sub_f32_e32 v0, v17, v199
	v_exp_f32_e32 v17, v0
	v_sub_f32_e32 v0, v18, v199
	v_exp_f32_e32 v18, v0
	v_sub_f32_e32 v0, v19, v199
	v_exp_f32_e32 v19, v0
	v_sub_f32_e32 v0, v20, v199
	v_exp_f32_e32 v20, v0
	v_sub_f32_e32 v0, v21, v199
	v_exp_f32_e32 v21, v0
	v_sub_f32_e32 v0, v22, v199
	v_exp_f32_e32 v22, v0
	v_sub_f32_e32 v0, v23, v199
	v_exp_f32_e32 v23, v0
	v_sub_f32_e32 v0, v24, v199
	v_exp_f32_e32 v24, v0
	v_sub_f32_e32 v0, v25, v199
	v_exp_f32_e32 v25, v0
	v_sub_f32_e32 v0, v26, v199
	v_exp_f32_e32 v26, v0
	v_sub_f32_e32 v0, v27, v199
	v_exp_f32_e32 v27, v0
	v_sub_f32_e32 v0, v28, v199
	v_exp_f32_e32 v28, v0
	v_sub_f32_e32 v0, v29, v199
	v_exp_f32_e32 v29, v0
	v_sub_f32_e32 v0, v30, v199
	v_exp_f32_e32 v30, v0
	v_sub_f32_e32 v0, v31, v199
	v_exp_f32_e32 v31, v0
	v_sub_f32_e32 v0, v32, v199
	v_exp_f32_e32 v80, v0
	v_sub_f32_e32 v0, v33, v199
	v_exp_f32_e32 v81, v0
	v_sub_f32_e32 v0, v34, v199
	v_exp_f32_e32 v82, v0
	v_sub_f32_e32 v0, v35, v199
	v_exp_f32_e32 v83, v0
	v_sub_f32_e32 v0, v36, v199
	v_exp_f32_e32 v84, v0
	v_sub_f32_e32 v0, v37, v199
	v_exp_f32_e32 v85, v0
	v_sub_f32_e32 v0, v38, v199
	v_exp_f32_e32 v86, v0
	v_sub_f32_e32 v0, v39, v199
	v_exp_f32_e32 v87, v0
	v_sub_f32_e32 v0, v40, v199
	v_exp_f32_e32 v88, v0
	v_sub_f32_e32 v0, v41, v199
	v_exp_f32_e32 v89, v0
	v_sub_f32_e32 v0, v42, v199
	v_exp_f32_e32 v90, v0
	v_sub_f32_e32 v0, v43, v199
	v_exp_f32_e32 v91, v0
	v_sub_f32_e32 v0, v44, v199
	v_exp_f32_e32 v92, v0
	v_sub_f32_e32 v0, v45, v199
	v_exp_f32_e32 v93, v0
	v_sub_f32_e32 v0, v46, v199
	v_exp_f32_e32 v94, v0
	v_sub_f32_e32 v0, v47, v199
	v_exp_f32_e32 v95, v0
	v_mov_b32_e32 v14, v1
	v_mov_b32_e32 v15, v1
	s_lshl_b32 s64, s4, 2
	v_xor_b32_e32 v48, 0x80000000, v199
	v_mov_b32_e32 v0, v1
	v_mov_b32_e32 v2, v1
	v_mov_b32_e32 v3, v1
	v_mov_b32_e32 v4, v1
	v_mov_b32_e32 v5, v1
	v_mov_b32_e32 v6, v1
	v_mov_b32_e32 v7, v1
	v_mov_b32_e32 v8, v1
	v_mov_b32_e32 v9, v1
	v_mov_b32_e32 v10, v1
	v_mov_b32_e32 v11, v1
	v_mov_b32_e32 v12, v1
	v_mov_b32_e32 v13, v1
	v_mov_b64_e32 v[46:47], v[14:15]
	v_mov_b64_e32 v[78:79], v[14:15]
	s_ashr_i32 s65, s63, 6
	v_mov_b32_e32 v49, v48
	v_mov_b32_e32 v50, v48
	v_mov_b32_e32 v51, v48
	v_mov_b32_e32 v52, v48
	v_mov_b32_e32 v53, v48
	v_mov_b32_e32 v54, v48
	v_mov_b32_e32 v55, v48
	v_mov_b32_e32 v56, v48
	v_mov_b32_e32 v57, v48
	v_mov_b32_e32 v58, v48
	v_mov_b32_e32 v59, v48
	v_mov_b32_e32 v60, v48
	v_mov_b32_e32 v61, v48
	v_mov_b32_e32 v62, v48
	v_mov_b32_e32 v63, v48
	s_or_b32 s66, s64, 3
	s_mov_b32 s67, 0
	v_mov_b32_e32 v201, 0
	s_movk_i32 s68, 0xbf
	v_mov_b64_e32 v[44:45], v[12:13]
	v_mov_b64_e32 v[42:43], v[10:11]
	v_mov_b64_e32 v[40:41], v[8:9]
	v_mov_b64_e32 v[38:39], v[6:7]
	v_mov_b64_e32 v[36:37], v[4:5]
	v_mov_b64_e32 v[34:35], v[2:3]
	v_mov_b64_e32 v[32:33], v[0:1]
	v_mov_b64_e32 v[76:77], v[12:13]
	v_mov_b64_e32 v[74:75], v[10:11]
	v_mov_b64_e32 v[72:73], v[8:9]
	v_mov_b64_e32 v[70:71], v[6:7]
	v_mov_b64_e32 v[68:69], v[4:5]
	v_mov_b64_e32 v[66:67], v[2:3]
	v_mov_b64_e32 v[64:65], v[0:1]
	s_bitcmp1_b32 s63, 7
	s_cbranch_scc1 .Latt_prio_done
	s_setprio 1
